# attention: canonicalising v_max x,x dropped from the per-tile row-max chain (4 instructions per tile on the chain in front of the rescale branch)
# baseline (speedup 1.0000x reference)
.LBB0_781:
	v_mov_b64_e32 v[66:67], s[10:11]
	v_mov_b64_e32 v[64:65], s[8:9]
	s_waitcnt lgkmcnt(8)
	v_mov_b32_e32 v64, v168
	v_mov_b32_e32 v65, v169
	v_add_u32_e32 v97, s6, v213
	s_nop 0
	v_mfma_f32_32x32x16_bf16 v[80:95], v[64:67], v[104:107], 0
	v_mov_b64_e32 v[66:67], s[10:11]
	v_mov_b64_e32 v[64:65], s[8:9]
	v_mov_b32_e32 v64, v170
	v_mov_b32_e32 v65, v171
	ds_read_b64_tr_b16 v[168:169], v97 offset:24576
	ds_read_b64_tr_b16 v[170:171], v97 offset:25088
	v_mfma_f32_32x32x16_bf16 v[64:79], v[64:67], v[104:107], 0
	s_waitcnt lgkmcnt(9)
	v_mfma_f32_32x32x16_bf16 v[80:95], v[172:175], v[124:127], v[80:95]
	v_add_f32_e32 v120, v48, v49
	v_add_f32_e32 v120, v50, v120
	v_add_f32_e32 v120, v51, v120
	v_add_f32_e32 v120, v52, v120
	v_add_f32_e32 v120, v53, v120
	v_cvt_pk_bf16_f32 v136, v48, v49
	v_cvt_pk_bf16_f32 v137, v50, v51
	ds_read_b64_tr_b16 v[48:49], v97 offset:28672
	ds_read_b64_tr_b16 v[50:51], v97 offset:29184
	s_waitcnt lgkmcnt(10)
	v_mfma_f32_32x32x16_bf16 v[64:79], v[164:167], v[124:127], v[64:79]
	v_add_f32_e32 v120, v54, v120
	v_add_f32_e32 v120, v55, v120
	v_add_f32_e32 v120, v56, v120
	v_add_f32_e32 v120, v57, v120
	v_cvt_pk_bf16_f32 v138, v52, v53
	v_cvt_pk_bf16_f32 v139, v54, v55
	ds_read_b64_tr_b16 v[52:53], v97 offset:25600
	ds_read_b64_tr_b16 v[54:55], v97 offset:26112
	s_waitcnt lgkmcnt(11)
	v_mfma_f32_32x32x16_bf16 v[80:95], v[160:163], v[116:119], v[80:95]
	v_add_f32_e32 v120, v58, v120
	v_add_f32_e32 v120, v59, v120
	v_add_f32_e32 v120, v60, v120
	v_add_f32_e32 v120, v61, v120
	v_cvt_pk_bf16_f32 v132, v56, v57
	v_cvt_pk_bf16_f32 v133, v58, v59
	ds_read_b64_tr_b16 v[56:57], v97 offset:29696
	ds_read_b64_tr_b16 v[58:59], v97 offset:30208
	s_waitcnt lgkmcnt(12)
	v_mfma_f32_32x32x16_bf16 v[64:79], v[156:159], v[116:119], v[64:79]
	v_add_f32_e32 v120, v62, v120
	v_add_f32_e32 v120, v63, v120
	v_add_f32_e32 v120, v32, v120
	v_add_f32_e32 v120, v33, v120
	v_cvt_pk_bf16_f32 v134, v60, v61
	v_cvt_pk_bf16_f32 v135, v62, v63
	ds_read_b64_tr_b16 v[60:61], v97 offset:26624
	ds_read_b64_tr_b16 v[62:63], v97 offset:27136
	s_waitcnt lgkmcnt(13)
	v_mfma_f32_32x32x16_bf16 v[80:95], v[152:155], v[112:115], v[80:95]
	v_add_f32_e32 v120, v34, v120
	v_add_f32_e32 v120, v35, v120
	v_add_f32_e32 v120, v36, v120
	v_add_f32_e32 v120, v37, v120
	v_cvt_pk_bf16_f32 v128, v32, v33
	v_cvt_pk_bf16_f32 v129, v34, v35
	ds_read_b64_tr_b16 v[32:33], v97 offset:30720
	ds_read_b64_tr_b16 v[34:35], v97 offset:31232
	s_waitcnt lgkmcnt(14)
	v_mfma_f32_32x32x16_bf16 v[64:79], v[148:151], v[112:115], v[64:79]
	v_add_f32_e32 v120, v38, v120
	v_add_f32_e32 v120, v39, v120
	v_add_f32_e32 v120, v40, v120
	v_add_f32_e32 v120, v41, v120
	v_cvt_pk_bf16_f32 v130, v36, v37
	v_cvt_pk_bf16_f32 v131, v38, v39
	ds_read_b64_tr_b16 v[36:37], v97 offset:27648
	ds_read_b64_tr_b16 v[38:39], v97 offset:28160
	s_waitcnt lgkmcnt(14)
	v_mfma_f32_32x32x16_bf16 v[80:95], v[144:147], v[108:111], v[80:95]
	v_add_f32_e32 v120, v42, v120
	v_add_f32_e32 v120, v43, v120
	v_add_f32_e32 v120, v44, v120
	v_add_f32_e32 v144, v45, v120
	v_cvt_pk_bf16_f32 v120, v40, v41
	v_cvt_pk_bf16_f32 v121, v42, v43
	ds_read_b64_tr_b16 v[40:41], v97 offset:31744
	ds_read_b64_tr_b16 v[42:43], v97 offset:32256
	v_mfma_f32_32x32x16_bf16 v[64:79], v[140:143], v[108:111], v[64:79]
	v_add_f32_e32 v97, v46, v144
	v_add_f32_e32 v97, v47, v97
	v_add_f32_e32 v97, 0, v97
	v_cvt_pk_bf16_f32 v122, v44, v45
	v_cvt_pk_bf16_f32 v123, v46, v47
	v_lshl_add_u64 v[44:45], v[182:183], 0, s[52:53]
	s_add_i32 s6, s80, s23
	s_mov_b32 s7, m0
	s_mov_b32 m0, s6
	s_nop 0
	global_load_lds_dwordx4 v[44:45], off
	s_mov_b32 m0, s7
	v_lshl_add_u64 v[44:45], v[180:181], 0, s[52:53]
	s_add_i32 s6, s57, s24
	s_mov_b32 s7, m0
	s_mov_b32 m0, s6
	s_nop 0
	global_load_lds_dwordx4 v[44:45], off
	s_mov_b32 m0, s7
	v_max_f32_e32 v44, v80, v81
	v_max3_f32 v45, v82, v83, v65
	v_max3_f32 v44, v44, v64, v66
	v_max3_f32 v44, v44, v67, v84
	v_max3_f32 v45, v45, v86, v87
	v_max3_f32 v44, v44, v85, v68
	v_max3_f32 v45, v45, v70, v71
	v_max3_f32 v44, v44, v69, v88
	v_max3_f32 v45, v45, v90, v91
	v_max3_f32 v44, v44, v89, v72
	v_max3_f32 v45, v45, v74, v75
	v_max3_f32 v44, v44, v73, v92
	v_max3_f32 v45, v45, v94, v95
	v_max3_f32 v44, v44, v93, v76
	v_max3_f32 v45, v45, v78, v79
	v_max3_f32 v44, v44, v77, v45
	v_mov_b32_e32 v45, v44
	s_nop 1
	v_permlane32_swap_b32_e32 v44, v45
	v_max_f32_e32 v44, v44, v45
	v_cmp_lt_f32_e32 vcc, s17, v44
	s_cmp_lg_u64 vcc, 0
	v_add_f32_e32 v185, v96, v97
	s_cselect_b64 s[6:7], -1, 0
	s_cbranch_vccnz .LBB0_789

.LBB0_797:
	v_mov_b64_e32 v[66:67], s[10:11]
	v_mov_b64_e32 v[64:65], s[8:9]
	s_waitcnt lgkmcnt(8)
	v_mov_b32_e32 v64, v168
	v_mov_b32_e32 v65, v169
	v_add_u32_e32 v97, s56, v213
	s_nop 0
	v_mfma_f32_32x32x16_bf16 v[80:95], v[64:67], v[104:107], 0
	v_mov_b64_e32 v[66:67], s[10:11]
	v_mov_b64_e32 v[64:65], s[8:9]
	v_mov_b32_e32 v64, v170
	v_mov_b32_e32 v65, v171
	ds_read_b64_tr_b16 v[168:169], v97 offset:24576
	ds_read_b64_tr_b16 v[170:171], v97 offset:25088
	v_mfma_f32_32x32x16_bf16 v[64:79], v[64:67], v[104:107], 0
	v_add_f32_e32 v105, v48, v49
	v_add_f32_e32 v105, v50, v105
	v_add_f32_e32 v105, v51, v105
	v_add_f32_e32 v105, v52, v105
	v_add_f32_e32 v105, v53, v105
	v_cvt_pk_bf16_f32 v136, v48, v49
	v_cvt_pk_bf16_f32 v137, v50, v51
	s_waitcnt lgkmcnt(9)
	v_mfma_f32_32x32x16_bf16 v[80:95], v[172:175], v[124:127], v[80:95]
	ds_read_b64_tr_b16 v[172:173], v97 offset:28672
	ds_read_b64_tr_b16 v[174:175], v97 offset:29184
	s_waitcnt lgkmcnt(10)
	v_mfma_f32_32x32x16_bf16 v[64:79], v[164:167], v[124:127], v[64:79]
	v_add_f32_e32 v48, v54, v105
	v_add_f32_e32 v48, v55, v48
	v_add_f32_e32 v48, v56, v48
	v_add_f32_e32 v48, v57, v48
	v_cvt_pk_bf16_f32 v138, v52, v53
	v_cvt_pk_bf16_f32 v139, v54, v55
	ds_read_b64_tr_b16 v[124:125], v97 offset:25600
	ds_read_b64_tr_b16 v[126:127], v97 offset:26112
	v_add_f32_e32 v48, v58, v48
	v_add_f32_e32 v48, v59, v48
	v_add_f32_e32 v48, v60, v48
	v_add_f32_e32 v48, v61, v48
	v_cvt_pk_bf16_f32 v132, v56, v57
	v_cvt_pk_bf16_f32 v133, v58, v59
	s_waitcnt lgkmcnt(11)
	v_mfma_f32_32x32x16_bf16 v[80:95], v[160:163], v[116:119], v[80:95]
	ds_read_b64_tr_b16 v[160:161], v97 offset:29696
	ds_read_b64_tr_b16 v[162:163], v97 offset:30208
	s_waitcnt lgkmcnt(12)
	v_mfma_f32_32x32x16_bf16 v[64:79], v[156:159], v[116:119], v[64:79]
	v_add_f32_e32 v48, v62, v48
	v_add_f32_e32 v48, v63, v48
	v_add_f32_e32 v48, v32, v48
	v_add_f32_e32 v48, v33, v48
	v_cvt_pk_bf16_f32 v134, v60, v61
	v_cvt_pk_bf16_f32 v135, v62, v63
	ds_read_b64_tr_b16 v[116:117], v97 offset:26624
	ds_read_b64_tr_b16 v[118:119], v97 offset:27136
	v_add_f32_e32 v48, v34, v48
	v_add_f32_e32 v48, v35, v48
	v_add_f32_e32 v48, v36, v48
	v_add_f32_e32 v48, v37, v48
	v_cvt_pk_bf16_f32 v128, v32, v33
	v_cvt_pk_bf16_f32 v129, v34, v35
	s_waitcnt lgkmcnt(13)
	v_mfma_f32_32x32x16_bf16 v[80:95], v[152:155], v[112:115], v[80:95]
	ds_read_b64_tr_b16 v[152:153], v97 offset:30720
	ds_read_b64_tr_b16 v[154:155], v97 offset:31232
	s_waitcnt lgkmcnt(14)
	v_mfma_f32_32x32x16_bf16 v[64:79], v[148:151], v[112:115], v[64:79]
	v_add_f32_e32 v32, v38, v48
	v_add_f32_e32 v32, v39, v32
	v_add_f32_e32 v32, v40, v32
	v_add_f32_e32 v32, v41, v32
	v_cvt_pk_bf16_f32 v130, v36, v37
	v_cvt_pk_bf16_f32 v131, v38, v39
	ds_read_b64_tr_b16 v[112:113], v97 offset:27648
	ds_read_b64_tr_b16 v[114:115], v97 offset:28160
	v_add_f32_e32 v32, v42, v32
	v_add_f32_e32 v32, v43, v32
	v_add_f32_e32 v32, v44, v32
	v_add_f32_e32 v32, v45, v32
	v_cvt_pk_bf16_f32 v120, v40, v41
	v_cvt_pk_bf16_f32 v121, v42, v43
	s_waitcnt lgkmcnt(14)
	v_mfma_f32_32x32x16_bf16 v[80:95], v[144:147], v[108:111], v[80:95]
	ds_read_b64_tr_b16 v[144:145], v97 offset:31744
	ds_read_b64_tr_b16 v[146:147], v97 offset:32256
	v_mfma_f32_32x32x16_bf16 v[64:79], v[140:143], v[108:111], v[64:79]
	v_add_f32_e32 v32, v46, v32
	v_add_f32_e32 v32, v47, v32
	v_add_f32_e32 v97, 0, v32
	v_cvt_pk_bf16_f32 v122, v44, v45
	v_cvt_pk_bf16_f32 v123, v46, v47
	v_mov_b32_e32 v32, v207
	s_nop 0
	v_lshlrev_b32_e32 v47, 2, v32
	v_add_u32_e32 v32, 0xe0, v47
	v_add_u32_e32 v33, 0xc0, v47
	v_cmp_le_i32_e32 vcc, v32, v191
	v_add_u32_e32 v34, 0xc2, v47
	v_add_u32_e32 v35, 0xc3, v47
	v_cndmask_b32_e32 v32, v223, v64, vcc
	v_cmp_lt_i32_e32 vcc, v33, v191
	v_add_u32_e32 v36, 0xc8, v47
	v_add_u32_e32 v37, 0xc9, v47
	v_cndmask_b32_e32 v49, v223, v81, vcc
	v_cmp_le_i32_e32 vcc, v33, v191
	v_add_u32_e32 v33, 0xe1, v47
	v_add_u32_e32 v38, 0xca, v47
	v_cndmask_b32_e32 v48, v223, v80, vcc
	v_cmp_le_i32_e32 vcc, v33, v191
	v_add_u32_e32 v39, 0xcb, v47
	v_add_u32_e32 v40, 0xd0, v47
	v_cndmask_b32_e32 v33, v223, v65, vcc
	v_cmp_le_i32_e32 vcc, v34, v191
	v_add_u32_e32 v34, 0xe2, v47
	v_add_u32_e32 v41, 0xd1, v47
	v_cndmask_b32_e32 v50, v223, v82, vcc
	v_cmp_le_i32_e32 vcc, v34, v191
	v_add_u32_e32 v42, 0xd2, v47
	v_add_u32_e32 v43, 0xd3, v47
	v_cndmask_b32_e32 v34, v223, v66, vcc
	v_cmp_le_i32_e32 vcc, v35, v191
	v_add_u32_e32 v35, 0xe3, v47
	v_add_u32_e32 v44, 0xd8, v47
	v_cndmask_b32_e32 v51, v223, v83, vcc
	v_cmp_le_i32_e32 vcc, v35, v191
	v_add_u32_e32 v45, 0xd9, v47
	v_max_f32_e32 v64, v49, v49
	v_cndmask_b32_e32 v35, v223, v67, vcc
	v_cmp_le_i32_e32 vcc, v36, v191
	v_add_u32_e32 v36, 0xe8, v47
	v_max_f32_e32 v65, v48, v48
	v_cndmask_b32_e32 v52, v223, v84, vcc
	v_cmp_le_i32_e32 vcc, v36, v191
	v_max_f32_e32 v64, v65, v64
	v_add_u32_e32 v46, 0xda, v47
	v_cndmask_b32_e32 v36, v223, v68, vcc
	v_cmp_le_i32_e32 vcc, v37, v191
	v_add_u32_e32 v37, 0xe9, v47
	v_max3_f32 v65, v50, v51, v33
	v_cndmask_b32_e32 v53, v223, v85, vcc
	v_cmp_le_i32_e32 vcc, v37, v191
	v_max3_f32 v64, v64, v32, v34
	v_max3_f32 v64, v64, v35, v52
	v_cndmask_b32_e32 v37, v223, v69, vcc
	v_cmp_le_i32_e32 vcc, v38, v191
	v_add_u32_e32 v38, 0xea, v47
	v_add_u32_e32 v63, 0xdb, v47
	v_cndmask_b32_e32 v54, v223, v86, vcc
	v_cmp_le_i32_e32 vcc, v38, v191
	v_max3_f32 v64, v64, v53, v36
	s_nop 0
	v_cndmask_b32_e32 v38, v223, v70, vcc
	v_cmp_le_i32_e32 vcc, v39, v191
	v_add_u32_e32 v39, 0xeb, v47
	s_nop 0
	v_cndmask_b32_e32 v55, v223, v87, vcc
	v_cmp_le_i32_e32 vcc, v39, v191
	v_max3_f32 v65, v65, v54, v55
	s_nop 0
	v_cndmask_b32_e32 v39, v223, v71, vcc
	v_cmp_le_i32_e32 vcc, v40, v191
	v_add_u32_e32 v40, 0xf0, v47
	v_max3_f32 v65, v65, v38, v39
	v_cndmask_b32_e32 v56, v223, v88, vcc
	v_cmp_le_i32_e32 vcc, v40, v191
	v_max3_f32 v64, v64, v37, v56
	s_nop 0
	v_cndmask_b32_e32 v40, v223, v72, vcc
	v_cmp_le_i32_e32 vcc, v41, v191
	v_add_u32_e32 v41, 0xf1, v47
	s_nop 0
	v_cndmask_b32_e32 v57, v223, v89, vcc
	v_cmp_le_i32_e32 vcc, v41, v191
	v_max3_f32 v64, v64, v57, v40
	s_nop 0
	v_cndmask_b32_e32 v41, v223, v73, vcc
	v_cmp_le_i32_e32 vcc, v42, v191
	v_add_u32_e32 v42, 0xf2, v47
	s_nop 0
	v_cndmask_b32_e32 v58, v223, v90, vcc
	v_cmp_le_i32_e32 vcc, v42, v191
	s_nop 1
	v_cndmask_b32_e32 v42, v223, v74, vcc
	v_cmp_le_i32_e32 vcc, v43, v191
	v_add_u32_e32 v43, 0xf3, v47
	s_nop 0
	v_cndmask_b32_e32 v59, v223, v91, vcc
	v_cmp_le_i32_e32 vcc, v43, v191
	v_max3_f32 v65, v65, v58, v59
	s_nop 0
	v_cndmask_b32_e32 v43, v223, v75, vcc
	v_cmp_le_i32_e32 vcc, v44, v191
	v_add_u32_e32 v44, 0xf8, v47
	v_max3_f32 v65, v65, v42, v43
	v_cndmask_b32_e32 v60, v223, v92, vcc
	v_cmp_le_i32_e32 vcc, v44, v191
	v_max3_f32 v64, v64, v41, v60
	s_nop 0
	v_cndmask_b32_e32 v44, v223, v76, vcc
	v_cmp_le_i32_e32 vcc, v45, v191
	v_add_u32_e32 v45, 0xf9, v47
	s_nop 0
	v_cndmask_b32_e32 v61, v223, v93, vcc
	v_cmp_le_i32_e32 vcc, v45, v191
	v_max3_f32 v66, v64, v61, v44
	v_add_f32_e32 v64, v96, v97
	v_cndmask_b32_e32 v45, v223, v77, vcc
	v_cmp_le_i32_e32 vcc, v46, v191
	v_add_u32_e32 v46, 0xfa, v47
	v_add_u32_e32 v47, 0xfb, v47
	v_cndmask_b32_e32 v62, v223, v94, vcc
	v_cmp_le_i32_e32 vcc, v46, v191
	s_nop 1
	v_cndmask_b32_e32 v46, v223, v78, vcc
	v_cmp_le_i32_e32 vcc, v63, v191
	s_nop 1
	v_cndmask_b32_e32 v63, v223, v95, vcc
	v_cmp_le_i32_e32 vcc, v47, v191
	v_max3_f32 v65, v65, v62, v63
	s_nop 0
	v_cndmask_b32_e32 v47, v223, v79, vcc
	v_max3_f32 v65, v65, v46, v47
	v_max3_f32 v65, v66, v45, v65
	v_mov_b32_e32 v66, v65
	s_nop 1
	v_permlane32_swap_b32_e32 v65, v66
	v_max_f32_e32 v65, v65, v66
	v_cmp_lt_f32_e32 vcc, s17, v65
	s_cmp_lg_u64 vcc, 0
	s_cselect_b64 s[6:7], -1, 0
	s_cbranch_vccnz .LBB0_854

.LBB0_808:
	v_max_f32_e32 v44, v80, v81
	v_max3_f32 v45, v82, v83, v65
	v_max3_f32 v44, v44, v64, v66
	v_max3_f32 v44, v44, v67, v84
	v_max3_f32 v45, v45, v86, v87
	v_max3_f32 v44, v44, v85, v68
	v_max3_f32 v45, v45, v70, v71
	v_max3_f32 v44, v44, v69, v88
	v_max3_f32 v45, v45, v90, v91
	v_max3_f32 v44, v44, v89, v72
	v_max3_f32 v45, v45, v74, v75
	v_max3_f32 v44, v44, v73, v92
	v_max3_f32 v45, v45, v94, v95
	v_max3_f32 v44, v44, v93, v76
	v_max3_f32 v45, v45, v78, v79
	v_max3_f32 v44, v44, v77, v45
	v_mov_b32_e32 v45, v44
	s_nop 1
	v_permlane32_swap_b32_e32 v44, v45
	v_max_f32_e32 v44, v44, v45
	v_cmp_lt_f32_e32 vcc, s17, v44
	s_cmp_lg_u64 vcc, 0
	v_add_f32_e32 v251, v96, v97
	s_cselect_b64 s[6:7], -1, 0
	s_cbranch_vccnz .LBB0_848

.LBB0_819:
	v_add_f32_e32 v96, v251, v72
	v_max_f32_e32 v72, v48, v49
	v_max3_f32 v73, v50, v51, v33
	v_max3_f32 v72, v72, v32, v34
	v_max3_f32 v72, v72, v35, v52
	v_max3_f32 v73, v73, v54, v55
	v_max3_f32 v72, v72, v53, v36
	v_max3_f32 v73, v73, v38, v39
	v_max3_f32 v72, v72, v37, v56
	v_max3_f32 v73, v73, v58, v59
	v_max3_f32 v72, v72, v57, v40
	v_max3_f32 v73, v73, v42, v43
	v_max3_f32 v72, v72, v41, v60
	v_max3_f32 v73, v73, v62, v63
	v_max3_f32 v72, v72, v61, v44
	v_max3_f32 v73, v73, v46, v47
	v_max3_f32 v72, v72, v45, v73
	v_mov_b32_e32 v73, v72
	s_nop 1
	v_permlane32_swap_b32_e32 v72, v73
	v_max_f32_e32 v72, v72, v73
	v_cmp_lt_f32_e32 vcc, s17, v72
	s_cmp_lg_u64 vcc, 0
	s_cselect_b64 s[86:87], -1, 0
	s_cbranch_vccnz .LBB0_851
	v_cndmask_b32_e64 v72, 0, 1, s[88:89]
	v_cmp_ne_u32_e64 s[6:7], 1, v72
	s_andn2_b64 vcc, exec, s[88:89]
	s_cbranch_vccnz .LBB0_822
